# GEMM epilogues P8 and P1: the 8 per-row scale loads of a tile issued together (counted waits) instead of load+vmcnt(0) per row group; scan block-copy waves software pipelined (2 blocks in flight)
# speedup vs baseline: 1.0299x; 1.0035x over previous
; __device__ __forceinline__ bf16_t f2bf(float x) { return (bf16_t)(pk2(x, 0.f) & 0xffffu); }
; __device__ __forceinline__ u32x4 pack8(const float (&f)[8]) { u32x4 w; w.x = pk2(f[0], f[1]); w.y = pk2(f[2], f[3]); w.z = pk2(f[4], f[5]); w.w = pk2(f[6], f[7]); return w; }
;     __device__ __forceinline__ void operator()(const f32x4 (&acc)[2][2][4][2], const pg8::Unit& u, int wr, int wc, int fr, int fq) const {
;     ...
;             for (int m = 0; m < 4; ++m) {
;                 const int r = u.pm * 256 + ai * 128 + wr * 64 + m * 16 + fr;
;                 float rs = 1.f;
;                 if (MODE == 0 || MODE == 5) rs = rowscale[r];
;                 float ssq = 0.f;
; #pragma unroll
;                 for (int bj = 0; bj < 2; ++bj) {
;                     const int c0 = u.pn * 256 + bj * 128 + wc * 32 + 8 * fq;
;                     const f32x4 a0 = acc[ai][bj][m][0], a1 = acc[ai][bj][m][1];
;                     float v[8] = {a0[0], a0[1], a0[2], a0[3], a1[0], a1[1], a1[2], a1[3]};
;                     if (MODE == 0) {
; #pragma unroll
;                         for (int j = 0; j < 8; ++j) v[j] *= rs;
;                         if (u.pn == 4) {
;                             const int b = r >> 12, t = r & 4095, cc = wc * 32 + 8 * fq;
;                             bf16_t* vt = OT + (size_t)bj * ((size_t)16 * 128 * 4096) + ((size_t)(b * 128 + cc)) * 4096 + t;
; #pragma unroll
;                             for (int j = 0; j < 8; ++j) vt[(size_t)j * 4096] = f2bf(v[j]);
;                         } else {
;                             *(u32x4*)(O + (size_t)r * ldc + c0) = pack8(v);
;                         }
.LBB0_360:
	s_lshl_b32 s31, s52, 8
	s_add_i32 s31, s31, s62
	v_or_b32_e32 v148, s31, v157
	v_ashrrev_i32_e32 v149, 31, v148
	v_lshl_add_u64 v[150:151], v[148:149], 2, s[20:21]
	global_load_dword v249, v[150:151], off offset:64
	global_load_dword v250, v[150:151], off offset:128
	global_load_dword v251, v[150:151], off offset:192
	global_load_dword v252, v[150:151], off offset:512
	global_load_dword v253, v[150:151], off offset:576
	global_load_dword v254, v[150:151], off offset:640
	global_load_dword v255, v[150:151], off offset:704
	global_load_dword v150, v[150:151], off
	s_cmp_lg_u32 s6, 4
	v_lshl_or_b32 v146, s6, 8, v160
	s_cselect_b64 s[52:53], -1, 0
	s_mov_b64 s[6:7], -1
	s_and_b64 vcc, exec, s[52:53]
	v_ashrrev_i32_e32 v147, 31, v146
	s_waitcnt vmcnt(0)
	v_pk_mul_f32 v[152:153], v[124:125], v[150:151] op_sel_hi:[1,0]
	v_pk_mul_f32 v[126:127], v[126:127], v[150:151] op_sel_hi:[1,0]
	v_pk_mul_f32 v[124:125], v[120:121], v[150:151] op_sel_hi:[1,0]
	v_pk_mul_f32 v[122:123], v[122:123], v[150:151] op_sel_hi:[1,0]
	s_cbranch_vccz .LBB0_362
	v_mov_b64_e32 v[120:121], s[38:39]
	v_mad_i64_i32 v[120:121], s[6:7], v148, s71, v[120:121]
	v_cvt_pk_bf16_f32 v166, v152, v153
	v_cvt_pk_bf16_f32 v167, v126, v127
	v_cvt_pk_bf16_f32 v168, v124, v125
	v_cvt_pk_bf16_f32 v169, v122, v123
	v_lshl_add_u64 v[120:121], v[146:147], 1, v[120:121]
	global_store_dwordx4 v[120:121], v[166:169], off
	s_mov_b64 s[6:7], 0

;     __device__ __forceinline__ void operator()(const f32x4 (&acc)[2][2][4][2], const pg8::Unit& u, int wr, int wc, int fr, int fq) const {
;     ...
;                 const int r = u.pm * 256 + ai * 128 + wr * 64 + m * 16 + fr;
;                 float rs = 1.f;
;                 if (MODE == 0 || MODE == 5) rs = rowscale[r];
;     ...
;                         for (int j = 0; j < 8; ++j) v[j] *= rs;
.LBB0_368:
	v_or_b32_e32 v114, 16, v148
	v_ashrrev_i32_e32 v115, 31, v114
	v_lshl_add_u64 v[116:117], v[114:115], 2, s[20:21]
	v_mov_b32_e32 v116, v249
	s_and_b64 vcc, exec, s[6:7]
	s_mov_b64 s[52:53], -1
	v_pk_mul_f32 v[118:119], v[108:109], v[116:117] op_sel_hi:[1,0]
	v_pk_mul_f32 v[110:111], v[110:111], v[116:117] op_sel_hi:[1,0]
	v_pk_mul_f32 v[108:109], v[104:105], v[116:117] op_sel_hi:[1,0]
	v_pk_mul_f32 v[104:105], v[106:107], v[116:117] op_sel_hi:[1,0]
	s_cbranch_vccnz .LBB0_370
	v_mov_b64_e32 v[106:107], s[38:39]
	v_mad_i64_i32 v[106:107], s[52:53], v114, s71, v[106:107]
	v_cvt_pk_bf16_f32 v122, v118, v119
	v_cvt_pk_bf16_f32 v123, v110, v111
	v_cvt_pk_bf16_f32 v124, v108, v109
	v_cvt_pk_bf16_f32 v125, v104, v105
	v_lshl_add_u64 v[106:107], v[146:147], 1, v[106:107]
	s_mov_b64 s[52:53], 0
	global_store_dwordx4 v[106:107], v[122:125], off

;     __device__ __forceinline__ void operator()(const f32x4 (&acc)[2][2][4][2], const pg8::Unit& u, int wr, int wc, int fr, int fq) const {
;     ...
;                 const int r = u.pm * 256 + ai * 128 + wr * 64 + m * 16 + fr;
;                 float rs = 1.f;
;                 if (MODE == 0 || MODE == 5) rs = rowscale[r];
;     ...
;                         for (int j = 0; j < 8; ++j) v[j] *= rs;
.LBB0_376:
	v_or_b32_e32 v96, 32, v148
	v_ashrrev_i32_e32 v97, 31, v96
	v_lshl_add_u64 v[98:99], v[96:97], 2, s[20:21]
	v_mov_b32_e32 v98, v250
	s_and_b64 vcc, exec, s[6:7]
	s_mov_b64 s[52:53], -1
	v_pk_mul_f32 v[100:101], v[92:93], v[98:99] op_sel_hi:[1,0]
	v_pk_mul_f32 v[94:95], v[94:95], v[98:99] op_sel_hi:[1,0]
	v_pk_mul_f32 v[92:93], v[88:89], v[98:99] op_sel_hi:[1,0]
	v_pk_mul_f32 v[88:89], v[90:91], v[98:99] op_sel_hi:[1,0]
	s_cbranch_vccnz .LBB0_378
	v_mov_b64_e32 v[90:91], s[38:39]
	v_mad_i64_i32 v[90:91], s[52:53], v96, s71, v[90:91]
	v_cvt_pk_bf16_f32 v102, v100, v101
	v_cvt_pk_bf16_f32 v103, v94, v95
	v_cvt_pk_bf16_f32 v104, v92, v93
	v_cvt_pk_bf16_f32 v105, v88, v89
	v_lshl_add_u64 v[90:91], v[146:147], 1, v[90:91]
	s_mov_b64 s[52:53], 0
	global_store_dwordx4 v[90:91], v[102:105], off

;     __device__ __forceinline__ void operator()(const f32x4 (&acc)[2][2][4][2], const pg8::Unit& u, int wr, int wc, int fr, int fq) const {
;     ...
;                 const int r = u.pm * 256 + ai * 128 + wr * 64 + m * 16 + fr;
;                 float rs = 1.f;
;                 if (MODE == 0 || MODE == 5) rs = rowscale[r];
;     ...
;                         for (int j = 0; j < 8; ++j) v[j] *= rs;
.LBB0_384:
	v_or_b32_e32 v80, 48, v148
	v_ashrrev_i32_e32 v81, 31, v80
	v_lshl_add_u64 v[82:83], v[80:81], 2, s[20:21]
	v_mov_b32_e32 v82, v251
	s_and_b64 vcc, exec, s[6:7]
	s_mov_b64 s[52:53], -1
	v_pk_mul_f32 v[84:85], v[76:77], v[82:83] op_sel_hi:[1,0]
	v_pk_mul_f32 v[78:79], v[78:79], v[82:83] op_sel_hi:[1,0]
	v_pk_mul_f32 v[76:77], v[72:73], v[82:83] op_sel_hi:[1,0]
	v_pk_mul_f32 v[72:73], v[74:75], v[82:83] op_sel_hi:[1,0]
	s_cbranch_vccnz .LBB0_386
	v_mov_b64_e32 v[74:75], s[38:39]
	v_mad_i64_i32 v[74:75], s[52:53], v80, s71, v[74:75]
	v_cvt_pk_bf16_f32 v86, v84, v85
	v_cvt_pk_bf16_f32 v87, v78, v79
	v_cvt_pk_bf16_f32 v88, v76, v77
	v_cvt_pk_bf16_f32 v89, v72, v73
	v_lshl_add_u64 v[74:75], v[146:147], 1, v[74:75]
	s_mov_b64 s[52:53], 0
	global_store_dwordx4 v[74:75], v[86:89], off

;     __device__ __forceinline__ void operator()(const f32x4 (&acc)[2][2][4][2], const pg8::Unit& u, int wr, int wc, int fr, int fq) const {
;     ...
;                 const int r = u.pm * 256 + ai * 128 + wr * 64 + m * 16 + fr;
;                 float rs = 1.f;
;                 if (MODE == 0 || MODE == 5) rs = rowscale[r];
;     ...
;                         for (int j = 0; j < 8; ++j) v[j] *= rs;
.LBB0_392:
	s_addk_i32 s31, 0x80
	v_or_b32_e32 v64, s31, v157
	v_ashrrev_i32_e32 v65, 31, v64
	v_lshl_add_u64 v[66:67], v[64:65], 2, s[20:21]
	v_mov_b32_e32 v66, v252
	s_and_b64 vcc, exec, s[6:7]
	s_mov_b64 s[52:53], -1
	v_pk_mul_f32 v[70:71], v[60:61], v[66:67] op_sel_hi:[1,0]
	v_pk_mul_f32 v[68:69], v[62:63], v[66:67] op_sel_hi:[1,0]
	v_pk_mul_f32 v[62:63], v[56:57], v[66:67] op_sel_hi:[1,0]
	v_pk_mul_f32 v[60:61], v[58:59], v[66:67] op_sel_hi:[1,0]
	s_cbranch_vccnz .LBB0_394
	v_mov_b64_e32 v[72:73], s[38:39]
	v_mad_i64_i32 v[72:73], s[52:53], v64, s71, v[72:73]
	v_cvt_pk_bf16_f32 v56, v70, v71
	v_cvt_pk_bf16_f32 v57, v68, v69
	v_cvt_pk_bf16_f32 v58, v62, v63
	v_cvt_pk_bf16_f32 v59, v60, v61
	v_lshl_add_u64 v[72:73], v[146:147], 1, v[72:73]
	s_mov_b64 s[52:53], 0
	global_store_dwordx4 v[72:73], v[56:59], off

;     __device__ __forceinline__ void operator()(const f32x4 (&acc)[2][2][4][2], const pg8::Unit& u, int wr, int wc, int fr, int fq) const {
;     ...
;                 const int r = u.pm * 256 + ai * 128 + wr * 64 + m * 16 + fr;
;                 float rs = 1.f;
;                 if (MODE == 0 || MODE == 5) rs = rowscale[r];
;     ...
;                         for (int j = 0; j < 8; ++j) v[j] *= rs;
.LBB0_400:
	v_or_b32_e32 v50, 16, v64
	v_ashrrev_i32_e32 v51, 31, v50
	v_lshl_add_u64 v[52:53], v[50:51], 2, s[20:21]
	v_mov_b32_e32 v52, v253
	s_and_b64 vcc, exec, s[6:7]
	s_mov_b64 s[52:53], -1
	v_pk_mul_f32 v[54:55], v[44:45], v[52:53] op_sel_hi:[1,0]
	v_pk_mul_f32 v[46:47], v[46:47], v[52:53] op_sel_hi:[1,0]
	v_pk_mul_f32 v[44:45], v[40:41], v[52:53] op_sel_hi:[1,0]
	v_pk_mul_f32 v[40:41], v[42:43], v[52:53] op_sel_hi:[1,0]
	s_cbranch_vccnz .LBB0_402
	v_mov_b64_e32 v[42:43], s[38:39]
	v_mad_i64_i32 v[42:43], s[52:53], v50, s71, v[42:43]
	v_cvt_pk_bf16_f32 v58, v54, v55
	v_cvt_pk_bf16_f32 v59, v46, v47
	v_cvt_pk_bf16_f32 v60, v44, v45
	v_cvt_pk_bf16_f32 v61, v40, v41
	v_lshl_add_u64 v[42:43], v[146:147], 1, v[42:43]
	s_mov_b64 s[52:53], 0
	global_store_dwordx4 v[42:43], v[58:61], off

;     __device__ __forceinline__ void operator()(const f32x4 (&acc)[2][2][4][2], const pg8::Unit& u, int wr, int wc, int fr, int fq) const {
;     ...
;                 const int r = u.pm * 256 + ai * 128 + wr * 64 + m * 16 + fr;
;                 float rs = 1.f;
;                 if (MODE == 0 || MODE == 5) rs = rowscale[r];
;     ...
;                         for (int j = 0; j < 8; ++j) v[j] *= rs;
.LBB0_408:
	v_or_b32_e32 v32, 32, v64
	v_ashrrev_i32_e32 v33, 31, v32
	v_lshl_add_u64 v[34:35], v[32:33], 2, s[20:21]
	v_mov_b32_e32 v34, v254
	s_and_b64 vcc, exec, s[6:7]
	s_mov_b64 s[52:53], -1
	v_pk_mul_f32 v[36:37], v[28:29], v[34:35] op_sel_hi:[1,0]
	v_pk_mul_f32 v[30:31], v[30:31], v[34:35] op_sel_hi:[1,0]
	v_pk_mul_f32 v[28:29], v[24:25], v[34:35] op_sel_hi:[1,0]
	v_pk_mul_f32 v[24:25], v[26:27], v[34:35] op_sel_hi:[1,0]
	s_cbranch_vccnz .LBB0_410
	v_mov_b64_e32 v[26:27], s[38:39]
	v_mad_i64_i32 v[26:27], s[52:53], v32, s71, v[26:27]
	v_cvt_pk_bf16_f32 v38, v36, v37
	v_cvt_pk_bf16_f32 v39, v30, v31
	v_cvt_pk_bf16_f32 v40, v28, v29
	v_cvt_pk_bf16_f32 v41, v24, v25
	v_lshl_add_u64 v[26:27], v[146:147], 1, v[26:27]
	s_mov_b64 s[52:53], 0
	global_store_dwordx4 v[26:27], v[38:41], off

;     __device__ __forceinline__ void operator()(const f32x4 (&acc)[2][2][4][2], const pg8::Unit& u, int wr, int wc, int fr, int fq) const {
;     ...
;                 const int r = u.pm * 256 + ai * 128 + wr * 64 + m * 16 + fr;
;                 float rs = 1.f;
;                 if (MODE == 0 || MODE == 5) rs = rowscale[r];
;     ...
;                         for (int j = 0; j < 8; ++j) v[j] *= rs;
.LBB0_416:
	v_or_b32_e32 v16, 48, v64
	v_ashrrev_i32_e32 v17, 31, v16
	v_lshl_add_u64 v[18:19], v[16:17], 2, s[20:21]
	v_mov_b32_e32 v18, v255
	s_and_b64 vcc, exec, s[6:7]
	s_mov_b64 s[52:53], -1
	v_pk_mul_f32 v[20:21], v[12:13], v[18:19] op_sel_hi:[1,0]
	v_pk_mul_f32 v[14:15], v[14:15], v[18:19] op_sel_hi:[1,0]
	v_pk_mul_f32 v[12:13], v[8:9], v[18:19] op_sel_hi:[1,0]
	v_pk_mul_f32 v[8:9], v[10:11], v[18:19] op_sel_hi:[1,0]
	s_cbranch_vccnz .LBB0_418
	v_mov_b64_e32 v[10:11], s[38:39]
	v_mad_i64_i32 v[10:11], s[52:53], v16, s71, v[10:11]
	v_cvt_pk_bf16_f32 v22, v20, v21
	v_cvt_pk_bf16_f32 v23, v14, v15
	v_cvt_pk_bf16_f32 v24, v12, v13
	v_cvt_pk_bf16_f32 v25, v8, v9
	v_lshl_add_u64 v[10:11], v[146:147], 1, v[10:11]
	s_mov_b64 s[52:53], 0
	global_store_dwordx4 v[10:11], v[22:25], off

; #define LAS __attribute__((address_space(3)))
; __device__ __forceinline__ unsigned char* s2_block(unsigned char* ws, float* out, int c) {
;     if (c < 10699) return ws + WS_RC + (size_t)c * S2_CHB;
;     c -= 10699; if (c < 8024) return ws + WS_RA + (size_t)416 * MiB + (size_t)c * S2_CHB;
;     c -= 8024; if (c < 5349) return (unsigned char*)out + (size_t)192 * MiB + (size_t)c * S2_CHB;
;     c -= 5349; if (c < 2674) return ws + WS_LORAA + (size_t)c * S2_CHB;
;     c -= 2674; return ws + WS_END + (size_t)c * S2_CHB;
; }
; __device__ __forceinline__ void scan_phase(LAS unsigned char* lds, const Args& a, const bf16_t* z, const bf16_t* lo, float* yraw) {
;     ...
;             { const u32x4* src = (const u32x4*)s2_block(a.ws, a.out, c0 + pw); LAS unsigned char* dstl = lds + (0 * 4 + pw) * S2_CHB;
;               u32x4 tmp[13];
; #pragma unroll
;               for (int k = 0; k < 13; ++k) { const int idx = lane + 64 * k; if (idx < S2_CHB / 16) tmp[k] = src[idx]; }
; #pragma unroll
;               for (int k = 0; k < 13; ++k) { const int idx = lane + 64 * k; if (idx < S2_CHB / 16) *(LAS u32x4*)(dstl + idx * 16) = tmp[k]; } }
;             __syncthreads();
;             for (int it = 0; it < NIT; ++it) {
;                 if (it + 1 < NIT) { const u32x4* src = (const u32x4*)s2_block(a.ws, a.out, c0 + (it + 1) * 4 + pw); LAS unsigned char* dstl = lds + (((it + 1) & 1) * 4 + pw) * S2_CHB;
.LBB0_886:
	s_or_b64 exec, exec, s[24:25]
	v_add_u32_e32 v94, s33, v57
	s_waitcnt vmcnt(11)
	ds_write_b128 v94, v[32:35]
	v_add_u32_e32 v32, s33, v59
	s_waitcnt vmcnt(10)
	ds_write_b128 v32, v[20:23]
	v_add_u32_e32 v20, s33, v61
	s_waitcnt vmcnt(9)
	ds_write_b128 v20, v[12:15]
	v_add_u32_e32 v12, s33, v63
	s_waitcnt vmcnt(8)
	ds_write_b128 v12, v[8:11]
	v_add_u32_e32 v8, s33, v65
	s_waitcnt vmcnt(7)
	ds_write_b128 v8, v[24:27]
	v_add_u32_e32 v8, s33, v67
	s_waitcnt vmcnt(6)
	ds_write_b128 v8, v[16:19]
	v_add_u32_e32 v8, s33, v69
	s_waitcnt vmcnt(5)
	ds_write_b128 v8, v[36:39]
	v_add_u32_e32 v8, s33, v71
	s_waitcnt vmcnt(4)
	ds_write_b128 v8, v[28:31]
	v_add_u32_e32 v8, s33, v73
	s_waitcnt vmcnt(3)
	ds_write_b128 v8, v[44:47]
	v_add_u32_e32 v8, s33, v76
	s_waitcnt vmcnt(2)
	ds_write_b128 v8, v[40:43]
	v_add_u32_e32 v8, s33, v77
	s_waitcnt vmcnt(1)
	ds_write_b128 v8, v[52:55]
	v_add_u32_e32 v8, s33, v78
	s_waitcnt vmcnt(0)
	ds_write_b128 v8, v[48:51]
	s_and_saveexec_b64 s[22:23], s[4:5]
	v_add_u32_e32 v8, s33, v79
	ds_write_b128 v8, v[0:3]
	s_or_b64 exec, exec, s[22:23]
	s_mov_b32 s54, 4
	s_waitcnt lgkmcnt(0)
	s_barrier
	s_branch .LBB0_890
.LBB0_890:
	s_add_i32 s23, s40, s54
	s_add_i32 s22, s23, -4
	s_cmpk_gt_i32 s22, 0x29ca
	s_mov_b64 s[28:29], -1
	s_cbranch_scc0 .Lscp_904
	s_cmpk_gt_u32 s22, 0x4922
	s_cbranch_scc0 .Lscp_901
	s_cmpk_gt_u32 s22, 0x5e07
	s_cbranch_scc0 .Lscp_898
	s_cmpk_gt_u32 s22, 0x6879
	s_mov_b64 s[26:27], -1
	s_cbranch_scc0 .Lscp_895
	s_add_i32 s10, s23, 0xffff9782
	s_mov_b64 s[26:27], 0
	s_mov_b64 s[24:25], s[10:11]

; #define LAS __attribute__((address_space(3)))
; __device__ __forceinline__ void scan_phase(LAS unsigned char* lds, const Args& a, const bf16_t* z, const bf16_t* lo, float* yraw) {
;     ...
;                 if (it + 1 < NIT) { const u32x4* src = (const u32x4*)s2_block(a.ws, a.out, c0 + (it + 1) * 4 + pw); LAS unsigned char* dstl = lds + (((it + 1) & 1) * 4 + pw) * S2_CHB;
;                   u32x4 tmp[13];
; #pragma unroll
;                   for (int k = 0; k < 13; ++k) { const int idx = lane + 64 * k; if (idx < S2_CHB / 16) tmp[k] = src[idx]; }
; #pragma unroll
;                   for (int k = 0; k < 13; ++k) { const int idx = lane + 64 * k; if (idx < S2_CHB / 16) *(LAS u32x4*)(dstl + idx * 16) = tmp[k]; } }
.Lscp_906:
	s_mul_i32 s10, s25, 0x3100
	s_mul_hi_u32 s22, s24, 0x3100
	s_add_i32 s10, s22, s10
	s_mul_i32 s22, s24, 0x3100
	s_add_u32 s22, s26, s22
	s_addc_u32 s23, s27, s10
	global_load_dwordx4 v[52:55], v84, s[22:23]
	global_load_dwordx4 v[48:51], v84, s[22:23] offset:1024
	global_load_dwordx4 v[44:47], v84, s[22:23] offset:2048
	global_load_dwordx4 v[40:43], v84, s[22:23] offset:3072
	global_load_dwordx4 v[36:39], v85, s[22:23]
	global_load_dwordx4 v[32:35], v86, s[22:23]
	global_load_dwordx4 v[28:31], v87, s[22:23]
	global_load_dwordx4 v[24:27], v88, s[22:23]
	global_load_dwordx4 v[20:23], v89, s[22:23]
	global_load_dwordx4 v[16:19], v90, s[22:23]
	global_load_dwordx4 v[12:15], v91, s[22:23]
	global_load_dwordx4 v[8:11], v92, s[22:23]
	s_and_saveexec_b64 s[24:25], s[4:5]
	global_load_dwordx4 v[4:7], v93, s[22:23]
	s_or_b64 exec, exec, s[24:25]
.Lsc_top:
	s_add_i32 s54, s54, 4
	s_cmpk_eq_i32 s54, 0x100
	s_cbranch_scc1 .Lsc_lastA
	s_add_i32 s23, s40, s54
	s_add_i32 s22, s23, -4
	s_cmpk_gt_i32 s22, 0x29ca
	s_mov_b64 s[28:29], -1
	s_cbranch_scc0 .Lscb_904
	s_cmpk_gt_u32 s22, 0x4922
	s_cbranch_scc0 .Lscb_901
	s_cmpk_gt_u32 s22, 0x5e07
	s_cbranch_scc0 .Lscb_898
	s_cmpk_gt_u32 s22, 0x6879
	s_mov_b64 s[26:27], -1
	s_cbranch_scc0 .Lscb_895
	s_add_i32 s10, s23, 0xffff9782
	s_mov_b64 s[26:27], 0
	s_mov_b64 s[24:25], s[10:11]

; #define LAS __attribute__((address_space(3)))
; __device__ __forceinline__ void scan_phase(LAS unsigned char* lds, const Args& a, const bf16_t* z, const bf16_t* lo, float* yraw) {
;     ...
;                 if (it + 1 < NIT) { const u32x4* src = (const u32x4*)s2_block(a.ws, a.out, c0 + (it + 1) * 4 + pw); LAS unsigned char* dstl = lds + (((it + 1) & 1) * 4 + pw) * S2_CHB;
;                   u32x4 tmp[13];
; #pragma unroll
;                   for (int k = 0; k < 13; ++k) { const int idx = lane + 64 * k; if (idx < S2_CHB / 16) tmp[k] = src[idx]; }
; #pragma unroll
;                   for (int k = 0; k < 13; ++k) { const int idx = lane + 64 * k; if (idx < S2_CHB / 16) *(LAS u32x4*)(dstl + idx * 16) = tmp[k]; } }
;                 __syncthreads();
.Lscb_906:
	s_mul_i32 s10, s25, 0x3100
	s_mul_hi_u32 s22, s24, 0x3100
	s_add_i32 s10, s22, s10
	s_mul_i32 s22, s24, 0x3100
	s_add_u32 s22, s26, s22
	s_addc_u32 s23, s27, s10
	global_load_dwordx4 v[96:99], v84, s[22:23]
	global_load_dwordx4 v[100:103], v84, s[22:23] offset:1024
	global_load_dwordx4 v[104:107], v84, s[22:23] offset:2048
	global_load_dwordx4 v[108:111], v84, s[22:23] offset:3072
	global_load_dwordx4 v[112:115], v85, s[22:23]
	global_load_dwordx4 v[116:119], v86, s[22:23]
	global_load_dwordx4 v[120:123], v87, s[22:23]
	global_load_dwordx4 v[124:127], v88, s[22:23]
	global_load_dwordx4 v[128:131], v89, s[22:23]
	global_load_dwordx4 v[132:135], v90, s[22:23]
	global_load_dwordx4 v[136:139], v91, s[22:23]
	global_load_dwordx4 v[140:143], v92, s[22:23]
	s_and_saveexec_b64 s[24:25], s[4:5]
	global_load_dwordx4 v[144:147], v93, s[22:23]
	s_or_b64 exec, exec, s[24:25]
	s_add_i32 s10, s54, -4
	s_and_b32 s10, s10, 4
	s_add_i32 s10, s10, s3
	s_mulk_i32 s10, 0x3100
	v_add_u32_e32 v94, s10, v57
	s_waitcnt vmcnt(25)
	ds_write_b128 v94, v[52:55]
	v_add_u32_e32 v95, s10, v59
	s_waitcnt vmcnt(24)
	ds_write_b128 v95, v[48:51]
	v_add_u32_e32 v94, s10, v61
	s_waitcnt vmcnt(23)
	ds_write_b128 v94, v[44:47]
	v_add_u32_e32 v95, s10, v63
	s_waitcnt vmcnt(22)
	ds_write_b128 v95, v[40:43]
	v_add_u32_e32 v94, s10, v65
	s_waitcnt vmcnt(21)
	ds_write_b128 v94, v[36:39]
	v_add_u32_e32 v95, s10, v67
	s_waitcnt vmcnt(20)
	ds_write_b128 v95, v[32:35]
	v_add_u32_e32 v94, s10, v69
	s_waitcnt vmcnt(19)
	ds_write_b128 v94, v[28:31]
	v_add_u32_e32 v95, s10, v71
	s_waitcnt vmcnt(18)
	ds_write_b128 v95, v[24:27]
	v_add_u32_e32 v94, s10, v73
	s_waitcnt vmcnt(17)
	ds_write_b128 v94, v[20:23]
	v_add_u32_e32 v95, s10, v76
	s_waitcnt vmcnt(16)
	ds_write_b128 v95, v[16:19]
	v_add_u32_e32 v94, s10, v77
	s_waitcnt vmcnt(15)
	ds_write_b128 v94, v[12:15]
	v_add_u32_e32 v95, s10, v78
	s_waitcnt vmcnt(14)
	ds_write_b128 v95, v[8:11]
	v_add_u32_e32 v94, s10, v79
	s_waitcnt vmcnt(13)
	s_and_saveexec_b64 s[22:23], s[4:5]
	ds_write_b128 v94, v[4:7]
	s_or_b64 exec, exec, s[22:23]
	s_waitcnt lgkmcnt(0)
	s_barrier
	s_add_i32 s54, s54, 4
	s_cmpk_eq_i32 s54, 0x100
	s_cbranch_scc1 .Lsc_lastB
	s_add_i32 s23, s40, s54
	s_add_i32 s22, s23, -4
	s_cmpk_gt_i32 s22, 0x29ca
	s_mov_b64 s[28:29], -1
	s_cbranch_scc0 .Lsca_904
	s_cmpk_gt_u32 s22, 0x4922
	s_cbranch_scc0 .Lsca_901
	s_cmpk_gt_u32 s22, 0x5e07
	s_cbranch_scc0 .Lsca_898
	s_cmpk_gt_u32 s22, 0x6879
	s_mov_b64 s[26:27], -1
	s_cbranch_scc0 .Lsca_895
	s_add_i32 s10, s23, 0xffff9782
	s_mov_b64 s[26:27], 0
	s_mov_b64 s[24:25], s[10:11]

; #define LAS __attribute__((address_space(3)))
; __device__ __forceinline__ void scan_phase(LAS unsigned char* lds, const Args& a, const bf16_t* z, const bf16_t* lo, float* yraw) {
;     ...
;                 if (it + 1 < NIT) { const u32x4* src = (const u32x4*)s2_block(a.ws, a.out, c0 + (it + 1) * 4 + pw); LAS unsigned char* dstl = lds + (((it + 1) & 1) * 4 + pw) * S2_CHB;
;                   u32x4 tmp[13];
; #pragma unroll
;                   for (int k = 0; k < 13; ++k) { const int idx = lane + 64 * k; if (idx < S2_CHB / 16) tmp[k] = src[idx]; }
; #pragma unroll
;                   for (int k = 0; k < 13; ++k) { const int idx = lane + 64 * k; if (idx < S2_CHB / 16) *(LAS u32x4*)(dstl + idx * 16) = tmp[k]; } }
;                 __syncthreads();
.Lsca_906:
	s_mul_i32 s10, s25, 0x3100
	s_mul_hi_u32 s22, s24, 0x3100
	s_add_i32 s10, s22, s10
	s_mul_i32 s22, s24, 0x3100
	s_add_u32 s22, s26, s22
	s_addc_u32 s23, s27, s10
	global_load_dwordx4 v[52:55], v84, s[22:23]
	global_load_dwordx4 v[48:51], v84, s[22:23] offset:1024
	global_load_dwordx4 v[44:47], v84, s[22:23] offset:2048
	global_load_dwordx4 v[40:43], v84, s[22:23] offset:3072
	global_load_dwordx4 v[36:39], v85, s[22:23]
	global_load_dwordx4 v[32:35], v86, s[22:23]
	global_load_dwordx4 v[28:31], v87, s[22:23]
	global_load_dwordx4 v[24:27], v88, s[22:23]
	global_load_dwordx4 v[20:23], v89, s[22:23]
	global_load_dwordx4 v[16:19], v90, s[22:23]
	global_load_dwordx4 v[12:15], v91, s[22:23]
	global_load_dwordx4 v[8:11], v92, s[22:23]
	s_and_saveexec_b64 s[24:25], s[4:5]
	global_load_dwordx4 v[4:7], v93, s[22:23]
	s_or_b64 exec, exec, s[24:25]
	s_add_i32 s10, s54, -4
	s_and_b32 s10, s10, 4
	s_add_i32 s10, s10, s3
	s_mulk_i32 s10, 0x3100
	v_add_u32_e32 v94, s10, v57
	s_waitcnt vmcnt(25)
	ds_write_b128 v94, v[96:99]
	v_add_u32_e32 v95, s10, v59
	s_waitcnt vmcnt(24)
	ds_write_b128 v95, v[100:103]
	v_add_u32_e32 v94, s10, v61
	s_waitcnt vmcnt(23)
	ds_write_b128 v94, v[104:107]
	v_add_u32_e32 v95, s10, v63
	s_waitcnt vmcnt(22)
	ds_write_b128 v95, v[108:111]
	v_add_u32_e32 v94, s10, v65
	s_waitcnt vmcnt(21)
	ds_write_b128 v94, v[112:115]
	v_add_u32_e32 v95, s10, v67
	s_waitcnt vmcnt(20)
	ds_write_b128 v95, v[116:119]
	v_add_u32_e32 v94, s10, v69
	s_waitcnt vmcnt(19)
	ds_write_b128 v94, v[120:123]
	v_add_u32_e32 v95, s10, v71
	s_waitcnt vmcnt(18)
	ds_write_b128 v95, v[124:127]
	v_add_u32_e32 v94, s10, v73
	s_waitcnt vmcnt(17)
	ds_write_b128 v94, v[128:131]
	v_add_u32_e32 v95, s10, v76
	s_waitcnt vmcnt(16)
	ds_write_b128 v95, v[132:135]
	v_add_u32_e32 v94, s10, v77
	s_waitcnt vmcnt(15)
	ds_write_b128 v94, v[136:139]
	v_add_u32_e32 v95, s10, v78
	s_waitcnt vmcnt(14)
	ds_write_b128 v95, v[140:143]
	v_add_u32_e32 v94, s10, v79
	s_waitcnt vmcnt(13)
	s_and_saveexec_b64 s[22:23], s[4:5]
	ds_write_b128 v94, v[144:147]
	s_or_b64 exec, exec, s[22:23]
	s_waitcnt lgkmcnt(0)
	s_barrier
	s_branch .Lsc_top
.Lsc_lastA:
	s_add_i32 s10, s54, -4
	s_and_b32 s10, s10, 4
	s_add_i32 s10, s10, s3
	s_mulk_i32 s10, 0x3100
	v_add_u32_e32 v94, s10, v57
	s_waitcnt vmcnt(12)
	ds_write_b128 v94, v[52:55]
	v_add_u32_e32 v95, s10, v59
	s_waitcnt vmcnt(11)
	ds_write_b128 v95, v[48:51]
	v_add_u32_e32 v94, s10, v61
	s_waitcnt vmcnt(10)
	ds_write_b128 v94, v[44:47]
	v_add_u32_e32 v95, s10, v63
	s_waitcnt vmcnt(9)
	ds_write_b128 v95, v[40:43]
	v_add_u32_e32 v94, s10, v65
	s_waitcnt vmcnt(8)
	ds_write_b128 v94, v[36:39]
	v_add_u32_e32 v95, s10, v67
	s_waitcnt vmcnt(7)
	ds_write_b128 v95, v[32:35]
	v_add_u32_e32 v94, s10, v69
	s_waitcnt vmcnt(6)
	ds_write_b128 v94, v[28:31]
	v_add_u32_e32 v95, s10, v71
	s_waitcnt vmcnt(5)
	ds_write_b128 v95, v[24:27]
	v_add_u32_e32 v94, s10, v73
	s_waitcnt vmcnt(4)
	ds_write_b128 v94, v[20:23]
	v_add_u32_e32 v95, s10, v76
	s_waitcnt vmcnt(3)
	ds_write_b128 v95, v[16:19]
	v_add_u32_e32 v94, s10, v77
	s_waitcnt vmcnt(2)
	ds_write_b128 v94, v[12:15]
	v_add_u32_e32 v95, s10, v78
	s_waitcnt vmcnt(1)
	ds_write_b128 v95, v[8:11]
	v_add_u32_e32 v94, s10, v79
	s_waitcnt vmcnt(0)
	s_and_saveexec_b64 s[22:23], s[4:5]
	ds_write_b128 v94, v[4:7]
	s_or_b64 exec, exec, s[22:23]
	s_waitcnt lgkmcnt(0)
	s_barrier
	s_branch .LBB0_859
.Lsc_lastB:
	s_add_i32 s10, s54, -4
	s_and_b32 s10, s10, 4
	s_add_i32 s10, s10, s3
	s_mulk_i32 s10, 0x3100
	v_add_u32_e32 v94, s10, v57
	s_waitcnt vmcnt(12)
	ds_write_b128 v94, v[96:99]
	v_add_u32_e32 v95, s10, v59
	s_waitcnt vmcnt(11)
	ds_write_b128 v95, v[100:103]
	v_add_u32_e32 v94, s10, v61
	s_waitcnt vmcnt(10)
	ds_write_b128 v94, v[104:107]
	v_add_u32_e32 v95, s10, v63
	s_waitcnt vmcnt(9)
	ds_write_b128 v95, v[108:111]
	v_add_u32_e32 v94, s10, v65
	s_waitcnt vmcnt(8)
	ds_write_b128 v94, v[112:115]
	v_add_u32_e32 v95, s10, v67
	s_waitcnt vmcnt(7)
	ds_write_b128 v95, v[116:119]
	v_add_u32_e32 v94, s10, v69
	s_waitcnt vmcnt(6)
	ds_write_b128 v94, v[120:123]
	v_add_u32_e32 v95, s10, v71
	s_waitcnt vmcnt(5)
	ds_write_b128 v95, v[124:127]
	v_add_u32_e32 v94, s10, v73
	s_waitcnt vmcnt(4)
	ds_write_b128 v94, v[128:131]
	v_add_u32_e32 v95, s10, v76
	s_waitcnt vmcnt(3)
	ds_write_b128 v95, v[132:135]
	v_add_u32_e32 v94, s10, v77
	s_waitcnt vmcnt(2)
	ds_write_b128 v94, v[136:139]
	v_add_u32_e32 v95, s10, v78
	s_waitcnt vmcnt(1)
	ds_write_b128 v95, v[140:143]
	v_add_u32_e32 v94, s10, v79
	s_waitcnt vmcnt(0)
	s_and_saveexec_b64 s[22:23], s[4:5]
	ds_write_b128 v94, v[144:147]
	s_or_b64 exec, exec, s[22:23]
	s_waitcnt lgkmcnt(0)
	s_barrier
	s_branch .LBB0_859

; __device__ __forceinline__ u32x4 pack8(const float (&f)[8]) { u32x4 w; w.x = pk2(f[0], f[1]); w.y = pk2(f[2], f[3]); w.z = pk2(f[4], f[5]); w.w = pk2(f[6], f[7]); return w; }
;     __device__ __forceinline__ void operator()(const f32x4 (&acc)[2][2][4][2], const pg8::Unit& u, int wr, int wc, int fr, int fq) const {
;     ...
;             for (int m = 0; m < 4; ++m) {
;                 const int r = u.pm * 256 + ai * 128 + wr * 64 + m * 16 + fr;
;                 float rs = 1.f;
;                 if (MODE == 0 || MODE == 5) rs = rowscale[r];
;     ...
; #pragma unroll
;                         for (int j = 0; j < 8; ++j) { const float x = fmaxf(v[j] * rs, 0.f); v[j] = x * x; }
;                         *(u32x4*)(O + (size_t)r * ldc + c0) = pack8(v);
.LBB0_1647:
	v_lshl_add_u32 v146, s24, 8, v148
	v_ashrrev_i32_e32 v147, 31, v146
	v_lshl_add_u64 v[144:145], v[146:147], 2, s[10:11]
	global_load_dword v248, v[144:145], off
	global_load_dword v249, v[144:145], off offset:64
	global_load_dword v250, v[144:145], off offset:128
	global_load_dword v251, v[144:145], off offset:192
	global_load_dword v252, v[144:145], off offset:512
	global_load_dword v253, v[144:145], off offset:576
	global_load_dword v254, v[144:145], off offset:640
	global_load_dword v255, v[144:145], off offset:704
	v_lshl_or_b32 v144, s50, 8, v150
	v_ashrrev_i32_e32 v145, 31, v144
	v_lshlrev_b64 v[160:161], 13, v[146:147]
	v_lshlrev_b64 v[144:145], 1, v[144:145]
	v_lshl_add_u64 v[160:161], s[38:39], 0, v[160:161]
	v_or_b32_e32 v154, 16, v146
	v_lshl_add_u64 v[160:161], v[160:161], 0, v[144:145]
	v_ashrrev_i32_e32 v155, 31, v154
	v_lshl_add_u64 v[162:163], v[154:155], 2, s[10:11]
	s_andn2_b64 vcc, exec, s[4:5]
	s_mov_b64 s[4:5], -1
	s_waitcnt vmcnt(7)
	v_mul_f32_e32 v124, v124, v248
	v_mul_f32_e32 v125, v125, v248
	v_mul_f32_e32 v126, v126, v248
	v_mul_f32_e32 v127, v127, v248
	v_mul_f32_e32 v120, v120, v248
	v_mul_f32_e32 v121, v121, v248
	v_mul_f32_e32 v122, v122, v248
	v_mul_f32_e32 v123, v123, v248
	v_mul_f32_e32 v147, v116, v248
	v_mul_f32_e32 v159, v117, v248
	v_mul_f32_e32 v164, v118, v248
	v_mul_f32_e32 v165, v119, v248
	v_mul_f32_e32 v166, v112, v248
	v_mul_f32_e32 v167, v113, v248
	v_mul_f32_e32 v168, v114, v248
	v_mul_f32_e32 v157, v115, v248
	v_max_f32_e32 v112, 0, v124
	v_max_f32_e32 v113, 0, v125
	v_max_f32_e32 v114, 0, v126
	v_max_f32_e32 v115, 0, v127
	v_max_f32_e32 v116, 0, v120
	v_max_f32_e32 v117, 0, v121
	v_max_f32_e32 v118, 0, v122
	v_max_f32_e32 v119, 0, v123
	v_max_f32_e32 v120, 0, v147
	v_max_f32_e32 v121, 0, v159
	v_max_f32_e32 v122, 0, v164
	v_max_f32_e32 v123, 0, v165
	v_max_f32_e32 v124, 0, v166
	v_max_f32_e32 v125, 0, v167
	v_max_f32_e32 v126, 0, v168
	v_max_f32_e32 v127, 0, v157
	v_pk_mul_f32 v[112:113], v[112:113], v[112:113]
	v_pk_mul_f32 v[114:115], v[114:115], v[114:115]
	v_pk_mul_f32 v[116:117], v[116:117], v[116:117]
	v_pk_mul_f32 v[118:119], v[118:119], v[118:119]
	v_pk_mul_f32 v[120:121], v[120:121], v[120:121]
	v_pk_mul_f32 v[122:123], v[122:123], v[122:123]
	v_pk_mul_f32 v[124:125], v[124:125], v[124:125]
	v_pk_mul_f32 v[126:127], v[126:127], v[126:127]
	v_cvt_pk_bf16_f32 v112, v112, v113
	v_cvt_pk_bf16_f32 v113, v114, v115
	v_cvt_pk_bf16_f32 v114, v116, v117
	v_cvt_pk_bf16_f32 v115, v118, v119
	v_cvt_pk_bf16_f32 v116, v120, v121
	v_cvt_pk_bf16_f32 v117, v122, v123
	v_cvt_pk_bf16_f32 v118, v124, v125
	v_cvt_pk_bf16_f32 v119, v126, v127
	global_store_dwordx4 v[160:161], v[112:115], off
	global_store_dwordx4 v[160:161], v[116:119], off offset:256
	v_lshlrev_b64 v[114:115], 13, v[154:155]
	v_lshl_add_u64 v[114:115], s[38:39], 0, v[114:115]
	v_or_b32_e32 v112, 32, v146
	v_lshl_add_u64 v[114:115], v[114:115], 0, v[144:145]
	v_ashrrev_i32_e32 v113, 31, v112
	v_lshl_add_u64 v[116:117], v[112:113], 2, s[10:11]
	s_waitcnt vmcnt(8)
	v_mul_f32_e32 v108, v108, v249
	v_mul_f32_e32 v109, v109, v249
	v_mul_f32_e32 v110, v110, v249
	v_mul_f32_e32 v111, v111, v249
	v_mul_f32_e32 v104, v104, v249
	v_mul_f32_e32 v105, v105, v249
	v_mul_f32_e32 v106, v106, v249
	v_mul_f32_e32 v107, v107, v249
	v_mul_f32_e32 v119, v100, v249
	v_mul_f32_e32 v120, v101, v249
	v_mul_f32_e32 v121, v102, v249
	v_mul_f32_e32 v122, v103, v249
	v_mul_f32_e32 v123, v96, v249
	v_mul_f32_e32 v124, v97, v249
	v_mul_f32_e32 v125, v98, v249
	v_mul_f32_e32 v118, v99, v249
	v_max_f32_e32 v96, 0, v108
	v_max_f32_e32 v97, 0, v109
	v_max_f32_e32 v98, 0, v110
	v_max_f32_e32 v99, 0, v111
	v_max_f32_e32 v100, 0, v104
	v_max_f32_e32 v101, 0, v105
	v_max_f32_e32 v102, 0, v106
	v_max_f32_e32 v103, 0, v107
	v_max_f32_e32 v104, 0, v119
	v_max_f32_e32 v105, 0, v120
	v_max_f32_e32 v106, 0, v121
	v_max_f32_e32 v107, 0, v122
	v_max_f32_e32 v108, 0, v123
	v_max_f32_e32 v109, 0, v124
	v_max_f32_e32 v110, 0, v125
	v_max_f32_e32 v111, 0, v118
	v_pk_mul_f32 v[96:97], v[96:97], v[96:97]
	v_pk_mul_f32 v[98:99], v[98:99], v[98:99]
	v_pk_mul_f32 v[100:101], v[100:101], v[100:101]
	v_pk_mul_f32 v[102:103], v[102:103], v[102:103]
	v_pk_mul_f32 v[104:105], v[104:105], v[104:105]
	v_pk_mul_f32 v[106:107], v[106:107], v[106:107]
	v_pk_mul_f32 v[108:109], v[108:109], v[108:109]
	v_pk_mul_f32 v[110:111], v[110:111], v[110:111]
	v_cvt_pk_bf16_f32 v96, v96, v97
	v_cvt_pk_bf16_f32 v97, v98, v99
	v_cvt_pk_bf16_f32 v98, v100, v101
	v_cvt_pk_bf16_f32 v99, v102, v103
	v_cvt_pk_bf16_f32 v100, v104, v105
	v_cvt_pk_bf16_f32 v101, v106, v107
	v_cvt_pk_bf16_f32 v102, v108, v109
	v_cvt_pk_bf16_f32 v103, v110, v111
	global_store_dwordx4 v[114:115], v[96:99], off
	global_store_dwordx4 v[114:115], v[100:103], off offset:256
	v_lshlrev_b64 v[98:99], 13, v[112:113]
	v_lshl_add_u64 v[98:99], s[38:39], 0, v[98:99]
	v_or_b32_e32 v96, 48, v146
	v_lshl_add_u64 v[98:99], v[98:99], 0, v[144:145]
	v_ashrrev_i32_e32 v97, 31, v96
	v_lshl_add_u64 v[100:101], v[96:97], 2, s[10:11]
	s_waitcnt vmcnt(9)
; __device__ __forceinline__ u32x4 pack8(const float (&f)[8]) { u32x4 w; w.x = pk2(f[0], f[1]); w.y = pk2(f[2], f[3]); w.z = pk2(f[4], f[5]); w.w = pk2(f[6], f[7]); return w; }
;     __device__ __forceinline__ void operator()(const f32x4 (&acc)[2][2][4][2], const pg8::Unit& u, int wr, int wc, int fr, int fq) const {
;     ...
;             for (int m = 0; m < 4; ++m) {
;                 const int r = u.pm * 256 + ai * 128 + wr * 64 + m * 16 + fr;
;                 float rs = 1.f;
;                 if (MODE == 0 || MODE == 5) rs = rowscale[r];
;     ...
; #pragma unroll
;                         for (int j = 0; j < 8; ++j) { const float x = fmaxf(v[j] * rs, 0.f); v[j] = x * x; }
;                         *(u32x4*)(O + (size_t)r * ldc + c0) = pack8(v);
	v_mul_f32_e32 v92, v92, v250
	v_mul_f32_e32 v93, v93, v250
	v_mul_f32_e32 v94, v94, v250
	v_mul_f32_e32 v95, v95, v250
	v_mul_f32_e32 v88, v88, v250
	v_mul_f32_e32 v89, v89, v250
	v_mul_f32_e32 v90, v90, v250
	v_mul_f32_e32 v91, v91, v250
	v_mul_f32_e32 v103, v84, v250
	v_mul_f32_e32 v104, v85, v250
	v_mul_f32_e32 v105, v86, v250
	v_mul_f32_e32 v106, v87, v250
	v_mul_f32_e32 v107, v80, v250
	v_mul_f32_e32 v108, v81, v250
	v_mul_f32_e32 v109, v82, v250
	v_mul_f32_e32 v102, v83, v250
	v_max_f32_e32 v80, 0, v92
	v_max_f32_e32 v81, 0, v93
	v_max_f32_e32 v82, 0, v94
	v_max_f32_e32 v83, 0, v95
	v_max_f32_e32 v84, 0, v88
	v_max_f32_e32 v85, 0, v89
	v_max_f32_e32 v86, 0, v90
	v_max_f32_e32 v87, 0, v91
	v_max_f32_e32 v88, 0, v103
	v_max_f32_e32 v89, 0, v104
	v_max_f32_e32 v90, 0, v105
	v_max_f32_e32 v91, 0, v106
	v_max_f32_e32 v92, 0, v107
	v_max_f32_e32 v93, 0, v108
	v_max_f32_e32 v94, 0, v109
	v_max_f32_e32 v95, 0, v102
	v_pk_mul_f32 v[80:81], v[80:81], v[80:81]
	v_pk_mul_f32 v[82:83], v[82:83], v[82:83]
	v_pk_mul_f32 v[84:85], v[84:85], v[84:85]
	v_pk_mul_f32 v[86:87], v[86:87], v[86:87]
	v_pk_mul_f32 v[88:89], v[88:89], v[88:89]
	v_pk_mul_f32 v[90:91], v[90:91], v[90:91]
	v_pk_mul_f32 v[92:93], v[92:93], v[92:93]
	v_pk_mul_f32 v[94:95], v[94:95], v[94:95]
	v_cvt_pk_bf16_f32 v80, v80, v81
	v_cvt_pk_bf16_f32 v81, v82, v83
	v_cvt_pk_bf16_f32 v82, v84, v85
	v_cvt_pk_bf16_f32 v83, v86, v87
	v_cvt_pk_bf16_f32 v84, v88, v89
	v_cvt_pk_bf16_f32 v85, v90, v91
	v_cvt_pk_bf16_f32 v86, v92, v93
	v_cvt_pk_bf16_f32 v87, v94, v95
	global_store_dwordx4 v[98:99], v[80:83], off
	global_store_dwordx4 v[98:99], v[84:87], off offset:256
	v_lshlrev_b64 v[82:83], 13, v[96:97]
	v_lshl_add_u64 v[82:83], s[38:39], 0, v[82:83]
	v_add_u32_e32 v80, 0x80, v146
	v_lshl_add_u64 v[82:83], v[82:83], 0, v[144:145]
	v_ashrrev_i32_e32 v81, 31, v80
	v_lshl_add_u64 v[84:85], v[80:81], 2, s[10:11]
	s_waitcnt vmcnt(10)
	v_mul_f32_e32 v76, v76, v251
	v_mul_f32_e32 v77, v77, v251
	v_mul_f32_e32 v78, v78, v251
	v_mul_f32_e32 v79, v79, v251
	v_mul_f32_e32 v72, v72, v251
	v_mul_f32_e32 v73, v73, v251
	v_mul_f32_e32 v74, v74, v251
	v_mul_f32_e32 v75, v75, v251
	v_mul_f32_e32 v87, v68, v251
	v_mul_f32_e32 v88, v69, v251
	v_mul_f32_e32 v89, v70, v251
	v_mul_f32_e32 v90, v71, v251
	v_mul_f32_e32 v91, v64, v251
	v_mul_f32_e32 v92, v65, v251
	v_mul_f32_e32 v93, v66, v251
	v_mul_f32_e32 v86, v67, v251
	v_max_f32_e32 v64, 0, v76
	v_max_f32_e32 v65, 0, v77
	v_max_f32_e32 v66, 0, v78
	v_max_f32_e32 v67, 0, v79
	v_max_f32_e32 v68, 0, v72
	v_max_f32_e32 v69, 0, v73
	v_max_f32_e32 v70, 0, v74
	v_max_f32_e32 v71, 0, v75
	v_max_f32_e32 v72, 0, v87
	v_max_f32_e32 v73, 0, v88
	v_max_f32_e32 v74, 0, v89
	v_max_f32_e32 v75, 0, v90
	v_max_f32_e32 v76, 0, v91
	v_max_f32_e32 v77, 0, v92
	v_max_f32_e32 v78, 0, v93
	v_max_f32_e32 v79, 0, v86
	v_pk_mul_f32 v[64:65], v[64:65], v[64:65]
	v_pk_mul_f32 v[66:67], v[66:67], v[66:67]
	v_pk_mul_f32 v[68:69], v[68:69], v[68:69]
	v_pk_mul_f32 v[70:71], v[70:71], v[70:71]
	v_pk_mul_f32 v[72:73], v[72:73], v[72:73]
	v_pk_mul_f32 v[74:75], v[74:75], v[74:75]
	v_pk_mul_f32 v[76:77], v[76:77], v[76:77]
	v_pk_mul_f32 v[78:79], v[78:79], v[78:79]
	v_cvt_pk_bf16_f32 v64, v64, v65
	v_cvt_pk_bf16_f32 v65, v66, v67
	v_cvt_pk_bf16_f32 v66, v68, v69
	v_cvt_pk_bf16_f32 v67, v70, v71
	v_cvt_pk_bf16_f32 v68, v72, v73
	v_cvt_pk_bf16_f32 v69, v74, v75
	v_cvt_pk_bf16_f32 v70, v76, v77
	v_cvt_pk_bf16_f32 v71, v78, v79
	global_store_dwordx4 v[82:83], v[64:67], off
	global_store_dwordx4 v[82:83], v[68:71], off offset:256
	v_lshlrev_b64 v[66:67], 13, v[80:81]
	v_lshl_add_u64 v[66:67], s[38:39], 0, v[66:67]
	v_add_u32_e32 v64, 0x90, v146
	v_lshl_add_u64 v[66:67], v[66:67], 0, v[144:145]
	v_ashrrev_i32_e32 v65, 31, v64
	v_lshl_add_u64 v[68:69], v[64:65], 2, s[10:11]
	s_waitcnt vmcnt(11)
	v_mul_f32_e32 v60, v60, v252
	v_mul_f32_e32 v61, v61, v252
	v_mul_f32_e32 v62, v62, v252
	v_mul_f32_e32 v63, v63, v252
	v_mul_f32_e32 v56, v56, v252
	v_mul_f32_e32 v57, v57, v252
	v_mul_f32_e32 v58, v58, v252
	v_mul_f32_e32 v59, v59, v252
	v_mul_f32_e32 v71, v52, v252
	v_mul_f32_e32 v72, v53, v252
	v_mul_f32_e32 v73, v54, v252
	v_mul_f32_e32 v74, v55, v252
	v_mul_f32_e32 v75, v48, v252
	v_mul_f32_e32 v76, v49, v252
	v_mul_f32_e32 v77, v50, v252
	v_mul_f32_e32 v70, v51, v252
	v_max_f32_e32 v48, 0, v60
	v_max_f32_e32 v49, 0, v61
	v_max_f32_e32 v50, 0, v62
	v_max_f32_e32 v51, 0, v63
	v_max_f32_e32 v52, 0, v56
	v_max_f32_e32 v53, 0, v57
	v_max_f32_e32 v54, 0, v58
	v_max_f32_e32 v55, 0, v59
	v_max_f32_e32 v56, 0, v71
	v_max_f32_e32 v57, 0, v72
	v_max_f32_e32 v58, 0, v73
	v_max_f32_e32 v59, 0, v74
	v_max_f32_e32 v60, 0, v75
	v_max_f32_e32 v61, 0, v76
	v_max_f32_e32 v62, 0, v77
	v_max_f32_e32 v63, 0, v70
	v_pk_mul_f32 v[48:49], v[48:49], v[48:49]
	v_pk_mul_f32 v[50:51], v[50:51], v[50:51]
	v_pk_mul_f32 v[52:53], v[52:53], v[52:53]
	v_pk_mul_f32 v[54:55], v[54:55], v[54:55]
	v_pk_mul_f32 v[56:57], v[56:57], v[56:57]
	v_pk_mul_f32 v[58:59], v[58:59], v[58:59]
	v_pk_mul_f32 v[60:61], v[60:61], v[60:61]
	v_pk_mul_f32 v[62:63], v[62:63], v[62:63]
	v_cvt_pk_bf16_f32 v48, v48, v49
	v_cvt_pk_bf16_f32 v49, v50, v51
	v_cvt_pk_bf16_f32 v50, v52, v53
	v_cvt_pk_bf16_f32 v51, v54, v55
	v_cvt_pk_bf16_f32 v52, v56, v57
	v_cvt_pk_bf16_f32 v53, v58, v59
	v_cvt_pk_bf16_f32 v54, v60, v61
	v_cvt_pk_bf16_f32 v55, v62, v63
	global_store_dwordx4 v[66:67], v[48:51], off
	global_store_dwordx4 v[66:67], v[52:55], off offset:256
	v_lshlrev_b64 v[50:51], 13, v[64:65]
	v_lshl_add_u64 v[50:51], s[38:39], 0, v[50:51]
	v_add_u32_e32 v48, 0xa0, v146
	v_lshl_add_u64 v[50:51], v[50:51], 0, v[144:145]
	v_ashrrev_i32_e32 v49, 31, v48
	v_lshl_add_u64 v[52:53], v[48:49], 2, s[10:11]
	s_waitcnt vmcnt(12)
; __device__ __forceinline__ u32x4 pack8(const float (&f)[8]) { u32x4 w; w.x = pk2(f[0], f[1]); w.y = pk2(f[2], f[3]); w.z = pk2(f[4], f[5]); w.w = pk2(f[6], f[7]); return w; }
;     __device__ __forceinline__ void operator()(const f32x4 (&acc)[2][2][4][2], const pg8::Unit& u, int wr, int wc, int fr, int fq) const {
;     ...
;             for (int m = 0; m < 4; ++m) {
;                 const int r = u.pm * 256 + ai * 128 + wr * 64 + m * 16 + fr;
;                 float rs = 1.f;
;                 if (MODE == 0 || MODE == 5) rs = rowscale[r];
;     ...
; #pragma unroll
;                         for (int j = 0; j < 8; ++j) { const float x = fmaxf(v[j] * rs, 0.f); v[j] = x * x; }
;                         *(u32x4*)(O + (size_t)r * ldc + c0) = pack8(v);
	v_mul_f32_e32 v44, v44, v253
	v_mul_f32_e32 v45, v45, v253
	v_mul_f32_e32 v46, v46, v253
	v_mul_f32_e32 v47, v47, v253
	v_mul_f32_e32 v40, v40, v253
	v_mul_f32_e32 v41, v41, v253
	v_mul_f32_e32 v42, v42, v253
	v_mul_f32_e32 v43, v43, v253
	v_mul_f32_e32 v55, v36, v253
	v_mul_f32_e32 v56, v37, v253
	v_mul_f32_e32 v57, v38, v253
	v_mul_f32_e32 v58, v39, v253
	v_mul_f32_e32 v59, v32, v253
	v_mul_f32_e32 v60, v33, v253
	v_mul_f32_e32 v61, v34, v253
	v_mul_f32_e32 v54, v35, v253
	v_max_f32_e32 v32, 0, v44
	v_max_f32_e32 v33, 0, v45
	v_max_f32_e32 v34, 0, v46
	v_max_f32_e32 v35, 0, v47
	v_max_f32_e32 v36, 0, v40
	v_max_f32_e32 v37, 0, v41
	v_max_f32_e32 v38, 0, v42
	v_max_f32_e32 v39, 0, v43
	v_max_f32_e32 v40, 0, v55
	v_max_f32_e32 v41, 0, v56
	v_max_f32_e32 v42, 0, v57
	v_max_f32_e32 v43, 0, v58
	v_max_f32_e32 v44, 0, v59
	v_max_f32_e32 v45, 0, v60
	v_max_f32_e32 v46, 0, v61
	v_max_f32_e32 v47, 0, v54
	v_pk_mul_f32 v[32:33], v[32:33], v[32:33]
	v_pk_mul_f32 v[34:35], v[34:35], v[34:35]
	v_pk_mul_f32 v[36:37], v[36:37], v[36:37]
	v_pk_mul_f32 v[38:39], v[38:39], v[38:39]
	v_pk_mul_f32 v[40:41], v[40:41], v[40:41]
	v_pk_mul_f32 v[42:43], v[42:43], v[42:43]
	v_pk_mul_f32 v[44:45], v[44:45], v[44:45]
	v_pk_mul_f32 v[46:47], v[46:47], v[46:47]
	v_cvt_pk_bf16_f32 v32, v32, v33
	v_cvt_pk_bf16_f32 v33, v34, v35
	v_cvt_pk_bf16_f32 v34, v36, v37
	v_cvt_pk_bf16_f32 v35, v38, v39
	v_cvt_pk_bf16_f32 v36, v40, v41
	v_cvt_pk_bf16_f32 v37, v42, v43
	v_cvt_pk_bf16_f32 v38, v44, v45
	v_cvt_pk_bf16_f32 v39, v46, v47
	global_store_dwordx4 v[50:51], v[32:35], off
	global_store_dwordx4 v[50:51], v[36:39], off offset:256
	v_lshlrev_b64 v[34:35], 13, v[48:49]
	v_lshl_add_u64 v[34:35], s[38:39], 0, v[34:35]
	v_add_u32_e32 v32, 0xb0, v146
	v_lshl_add_u64 v[34:35], v[34:35], 0, v[144:145]
	v_ashrrev_i32_e32 v33, 31, v32
	v_lshl_add_u64 v[36:37], v[32:33], 2, s[10:11]
	s_waitcnt vmcnt(13)
	v_mul_f32_e32 v28, v28, v254
	v_mul_f32_e32 v29, v29, v254
	v_mul_f32_e32 v30, v30, v254
	v_mul_f32_e32 v31, v31, v254
	v_mul_f32_e32 v24, v24, v254
	v_mul_f32_e32 v25, v25, v254
	v_mul_f32_e32 v26, v26, v254
	v_mul_f32_e32 v27, v27, v254
	v_mul_f32_e32 v39, v20, v254
	v_mul_f32_e32 v40, v21, v254
	v_mul_f32_e32 v41, v22, v254
	v_mul_f32_e32 v42, v23, v254
	v_mul_f32_e32 v43, v16, v254
	v_mul_f32_e32 v44, v17, v254
	v_mul_f32_e32 v45, v18, v254
	v_mul_f32_e32 v38, v19, v254
	v_max_f32_e32 v16, 0, v28
	v_max_f32_e32 v17, 0, v29
	v_max_f32_e32 v18, 0, v30
	v_max_f32_e32 v19, 0, v31
	v_max_f32_e32 v20, 0, v24
	v_max_f32_e32 v21, 0, v25
	v_max_f32_e32 v22, 0, v26
	v_max_f32_e32 v23, 0, v27
	v_max_f32_e32 v24, 0, v39
	v_max_f32_e32 v25, 0, v40
	v_max_f32_e32 v26, 0, v41
	v_max_f32_e32 v27, 0, v42
	v_max_f32_e32 v28, 0, v43
	v_max_f32_e32 v29, 0, v44
	v_max_f32_e32 v30, 0, v45
	v_max_f32_e32 v31, 0, v38
	v_pk_mul_f32 v[16:17], v[16:17], v[16:17]
	v_pk_mul_f32 v[18:19], v[18:19], v[18:19]
	v_pk_mul_f32 v[20:21], v[20:21], v[20:21]
	v_pk_mul_f32 v[22:23], v[22:23], v[22:23]
	v_pk_mul_f32 v[24:25], v[24:25], v[24:25]
	v_pk_mul_f32 v[26:27], v[26:27], v[26:27]
	v_pk_mul_f32 v[28:29], v[28:29], v[28:29]
	v_pk_mul_f32 v[30:31], v[30:31], v[30:31]
	v_cvt_pk_bf16_f32 v16, v16, v17
	v_cvt_pk_bf16_f32 v17, v18, v19
	v_cvt_pk_bf16_f32 v18, v20, v21
	v_cvt_pk_bf16_f32 v19, v22, v23
	v_cvt_pk_bf16_f32 v20, v24, v25
	v_cvt_pk_bf16_f32 v21, v26, v27
	v_cvt_pk_bf16_f32 v22, v28, v29
	v_cvt_pk_bf16_f32 v23, v30, v31
	global_store_dwordx4 v[34:35], v[16:19], off
	global_store_dwordx4 v[34:35], v[20:23], off offset:256
	v_lshlrev_b64 v[16:17], 13, v[32:33]
	v_lshl_add_u64 v[16:17], s[38:39], 0, v[16:17]
	v_lshl_add_u64 v[16:17], v[16:17], 0, v[144:145]
	s_waitcnt vmcnt(14)
	v_mul_f32_e32 v12, v12, v255
	v_mul_f32_e32 v13, v13, v255
	v_mul_f32_e32 v14, v14, v255
	v_mul_f32_e32 v15, v15, v255
	v_mul_f32_e32 v8, v8, v255
	v_mul_f32_e32 v9, v9, v255
	v_mul_f32_e32 v10, v10, v255
	v_mul_f32_e32 v11, v11, v255
	v_mul_f32_e32 v19, v4, v255
	v_mul_f32_e32 v20, v5, v255
	v_mul_f32_e32 v21, v6, v255
	v_mul_f32_e32 v22, v7, v255
	v_mul_f32_e32 v23, v0, v255
	v_mul_f32_e32 v24, v1, v255
	v_mul_f32_e32 v25, v2, v255
	v_mul_f32_e32 v18, v3, v255
	v_max_f32_e32 v0, 0, v12
	v_max_f32_e32 v1, 0, v13
	v_max_f32_e32 v2, 0, v14
	v_max_f32_e32 v3, 0, v15
	v_max_f32_e32 v4, 0, v8
	v_max_f32_e32 v5, 0, v9
	v_max_f32_e32 v6, 0, v10
	v_max_f32_e32 v7, 0, v11
	v_max_f32_e32 v8, 0, v19
	v_max_f32_e32 v9, 0, v20
	v_max_f32_e32 v10, 0, v21
	v_max_f32_e32 v11, 0, v22
	v_max_f32_e32 v12, 0, v23
	v_max_f32_e32 v13, 0, v24
	v_max_f32_e32 v14, 0, v25
	v_max_f32_e32 v15, 0, v18
	v_pk_mul_f32 v[0:1], v[0:1], v[0:1]
	v_pk_mul_f32 v[2:3], v[2:3], v[2:3]
	v_pk_mul_f32 v[4:5], v[4:5], v[4:5]
	v_pk_mul_f32 v[6:7], v[6:7], v[6:7]
	v_pk_mul_f32 v[8:9], v[8:9], v[8:9]
	v_pk_mul_f32 v[10:11], v[10:11], v[10:11]
	v_pk_mul_f32 v[12:13], v[12:13], v[12:13]
	v_pk_mul_f32 v[14:15], v[14:15], v[14:15]
	v_cvt_pk_bf16_f32 v0, v0, v1
	v_cvt_pk_bf16_f32 v1, v2, v3
	v_cvt_pk_bf16_f32 v2, v4, v5
	v_cvt_pk_bf16_f32 v3, v6, v7
	v_cvt_pk_bf16_f32 v4, v8, v9
	v_cvt_pk_bf16_f32 v5, v10, v11
	v_cvt_pk_bf16_f32 v6, v12, v13
	v_cvt_pk_bf16_f32 v7, v14, v15
	global_store_dwordx4 v[16:17], v[0:3], off
	global_store_dwordx4 v[16:17], v[4:7], off offset:256
	s_cbranch_vccnz .LBB0_1636
	s_andn2_b64 vcc, exec, s[8:9]
	s_cbranch_vccnz .LBB0_1635
	s_barrier
	s_branch .LBB0_1635

; __global__ void __launch_bounds__(512, 2) hymba_fwd(Args a) {
	.amdhsa_kernel _Z9hymba_fwd4Args
		.amdhsa_group_segment_fixed_size 0
		.amdhsa_private_segment_fixed_size 0
		.amdhsa_kernarg_size 536
		.amdhsa_user_sgpr_count 2
		.amdhsa_user_sgpr_dispatch_ptr 0
		.amdhsa_user_sgpr_queue_ptr 0
		.amdhsa_user_sgpr_kernarg_segment_ptr 1
		.amdhsa_user_sgpr_dispatch_id 0
		.amdhsa_user_sgpr_kernarg_preload_length 0
		.amdhsa_user_sgpr_kernarg_preload_offset 0
		.amdhsa_user_sgpr_private_segment_size 0
		.amdhsa_uses_dynamic_stack 0
		.amdhsa_enable_private_segment 0
		.amdhsa_system_sgpr_workgroup_id_x 1
		.amdhsa_system_sgpr_workgroup_id_y 0
		.amdhsa_system_sgpr_workgroup_id_z 0
		.amdhsa_system_sgpr_workgroup_info 0
		.amdhsa_system_vgpr_workitem_id 2
		.amdhsa_next_free_vgpr 256
		.amdhsa_next_free_sgpr 98
		.amdhsa_accum_offset 256
		.amdhsa_reserve_vcc 1
		.amdhsa_float_round_mode_32 0
		.amdhsa_float_round_mode_16_64 0
		.amdhsa_float_denorm_mode_32 3
		.amdhsa_float_denorm_mode_16_64 3
		.amdhsa_dx10_clamp 1
		.amdhsa_ieee_mode 1
		.amdhsa_fp16_overflow 0
		.amdhsa_tg_split 0
		.amdhsa_exception_fp_ieee_invalid_op 0
		.amdhsa_exception_fp_denorm_src 0
		.amdhsa_exception_fp_ieee_div_zero 0
		.amdhsa_exception_fp_ieee_overflow 0
		.amdhsa_exception_fp_ieee_underflow 0
		.amdhsa_exception_fp_ieee_inexact 0
		.amdhsa_exception_int_div_zero 0
	.end_amdhsa_kernel

; __global__ void __launch_bounds__(512, 2) hymba_fwd(Args a) {
amdhsa.kernels:
  - .agpr_count:     0
    .args:
      - .offset:         0
        .size:           280
        .value_kind:     by_value
      - .offset:         280
        .size:           4
        .value_kind:     hidden_block_count_x
      - .offset:         284
        .size:           4
        .value_kind:     hidden_block_count_y
      - .offset:         288
        .size:           4
        .value_kind:     hidden_block_count_z
      - .offset:         292
        .size:           2
        .value_kind:     hidden_group_size_x
      - .offset:         294
        .size:           2
        .value_kind:     hidden_group_size_y
      - .offset:         296
        .size:           2
        .value_kind:     hidden_group_size_z
      - .offset:         298
        .size:           2
        .value_kind:     hidden_remainder_x
      - .offset:         300
        .size:           2
        .value_kind:     hidden_remainder_y
      - .offset:         302
        .size:           2
        .value_kind:     hidden_remainder_z
      - .offset:         320
        .size:           8
        .value_kind:     hidden_global_offset_x
      - .offset:         328
        .size:           8
        .value_kind:     hidden_global_offset_y
      - .offset:         336
        .size:           8
        .value_kind:     hidden_global_offset_z
      - .offset:         344
        .size:           2
        .value_kind:     hidden_grid_dims
      - .offset:         368
        .size:           8
        .value_kind:     hidden_multigrid_sync_arg
      - .offset:         400
        .size:           4
        .value_kind:     hidden_dynamic_lds_size
    .group_segment_fixed_size: 0
    .kernarg_segment_align: 8
    .kernarg_segment_size: 536
    .language:       OpenCL C
    .language_version:
      - 2
      - 0
    .max_flat_workgroup_size: 512
    .name:           _Z9hymba_fwd4Args
    .private_segment_fixed_size: 0
    .sgpr_count:     104
    .sgpr_spill_count: 110
    .symbol:         _Z9hymba_fwd4Args.kd
    .uniform_work_group_size: 1
    .uses_dynamic_stack: false
    .vgpr_count:     256
    .vgpr_spill_count: 0
    .wavefront_size: 64
